# static s_setprio 1 for waves 4-7 during GEMM phases, no per-segment priority changes
# baseline (speedup 1.0000x reference)
; #define PG8_STAGE(bufoff, gbase, voff) do { _Pragma("unroll") for (int _i = 0; _i < 2; ++_i) \
;         __builtin_amdgcn_global_load_lds((const unsigned*)((const char*)(gbase) + (voff)[_i]), (PG8_LAS unsigned*)(lds + (bufoff) + ldsw + _i * 8192), 16, 0, 0); } while (0)
; #define PG8_WAIT_V(n) asm volatile("s_waitcnt vmcnt(" #n ")" ::: "memory")
; #define PG8_BAR __builtin_amdgcn_s_barrier()
; template <class Epi, class Sched, bool ALIGN_EPI = false, bool SP2 = false>
; __device__ __forceinline__ void gemm_phase(PG8_LAS unsigned char* lds, const Gemm g, const Sched& S, const Epi& E) {
;     ...
;     const char* cA = (const char*)g.A + (size_t)cur.pm * tstepA; const char* cB = (const char*)g.Bt + (size_t)cur.pn * tstepB;
;     S.a_ready(cur);
;     if constexpr (SP2) {
;         PG8_STAGE(PG8_SB(0, 0), cB, voffB); PG8_STAGE(PG8_SB(0, 1), cB + hstepB, voffB); PG8_STAGE(PG8_SA(0, 0), cA, voffA); PG8_STAGE(PG8_SA(0, 1), cA + hstepA, voffA);
;         if (wr == 1) PG8_BAR;
;         PG8_WAIT_V(2); PG8_BAR;
;         PG8_STAGE(PG8_SB(1, 0), cB + kstepB, voffB); PG8_STAGE(PG8_SA(1, 0), cA + kstepA, voffA); PG8_STAGE(PG8_SB(1, 1), cB + hstepB + kstepB, voffB);
;         PG8_WAIT_V(6); PG8_BAR;
.LBB0_155:
	s_and_b32 s4, s2, 3
	s_lshl_b32 s98, s3, 6
	v_and_b32_e32 v11, 48, v4
	s_lshl_b32 s2, s3, 13
	v_lshlrev_b32_e32 v12, 6, v4
	s_movk_i32 s3, 0x3c0
	v_lshlrev_b32_e32 v4, 2, v4
	v_and_or_b32 v11, v12, s3, v11
	v_and_b32_e32 v4, 32, v4
	v_bitop3_b32 v12, v11, s2, v4 bitop3:0xde
	v_writelane_b32 v255, s4, 44
	s_lshl_b32 s2, s4, 12
	v_bitop3_b32 v97, v11, s2, v4 bitop3:0xde
	v_readlane_b32 s2, v255, 7
	s_lshl_b32 s4, s2, 6
	s_lshl_b64 s[2:3], s[4:5], 2
	s_add_u32 s97, s78, s2
	s_addc_u32 s38, s79, s3
	s_add_u32 s31, s80, s2
	s_addc_u32 s6, s81, s3
	s_lshl_b32 s2, -1, s58
	s_add_i32 m0, s22, 0x18000
	v_lshl_add_u64 v[2:3], v[2:3], 0, s[36:37]
	s_not_b32 s99, s2
	v_readfirstlane_b32 s100, v232
	s_nop 3
	s_cmp_ge_u32 s100, 0x100
	s_cbranch_scc0 .Lsp_skip0
	s_setprio 1
.Lsp_skip0:
	s_waitcnt vmcnt(2)
	s_barrier
	global_load_lds_dwordx4 v[2:3], off
	s_add_i32 m0, s22, 0x1a000
	s_add_u32 s2, s24, 0x400000
	v_mov_b32_e32 v131, v96
	v_lshl_add_u64 v[0:1], v[0:1], 0, s[36:37]
	s_addc_u32 s3, s25, 0
	s_add_i32 s11, s22, 0x8000
	v_mov_b32_e32 v135, v96
	global_load_lds_dwordx4 v[0:1], off
	v_lshl_add_u64 v[0:1], s[2:3], 0, v[130:131]
	s_mov_b32 m0, s11
	s_add_i32 s19, s22, 0xa000
	global_load_lds_dwordx4 v[0:1], off
	v_lshl_add_u64 v[0:1], s[2:3], 0, v[134:135]
	s_add_u32 s2, s0, 0x40080
	s_mov_b32 m0, s19
	s_addc_u32 s3, s1, 0
	global_load_lds_dwordx4 v[0:1], off
	s_add_i32 m0, s22, 0x1c000
	v_lshl_add_u64 v[0:1], s[2:3], 0, v[132:133]
	global_load_lds_dwordx4 v[0:1], off
	v_lshl_add_u64 v[0:1], s[2:3], 0, v[136:137]
	s_add_i32 m0, s22, 0x1e000
	s_cmpk_lt_u32 s26, 0x100
	global_load_lds_dwordx4 v[0:1], off
	v_lshlrev_b32_e32 v0, 10, v8
	v_and_b32_e32 v0, 0xfffff800, v0
	v_lshl_add_u32 v0, v9, 7, v0
	v_and_b32_e32 v1, 1, v8
	v_lshl_or_b32 v0, v1, 6, v0
	v_lshl_add_u32 v138, v10, 1, v0
	v_lshlrev_b32_e32 v0, 10, v5
	s_cselect_b64 s[2:3], -1, 0
	v_and_b32_e32 v0, 0xfffff800, v0
	s_waitcnt vmcnt(6)
	v_writelane_b32 v255, s2, 45
	v_lshl_add_u32 v0, v6, 7, v0
	v_and_b32_e32 v1, 1, v5
	v_writelane_b32 v255, s3, 46
	v_lshl_or_b32 v0, v1, 6, v0
	v_readlane_b32 s2, v254, 25
	v_mov_b32_e32 v139, v96
	v_lshl_add_u32 v140, v7, 1, v0
	v_mov_b32_e32 v141, v96
	s_mov_b32 s53, 0
	v_add_u32_e32 v161, 0, v12
	s_mov_b32 s26, s2
	v_readlane_b32 s4, v254, 9
	s_barrier
	v_readlane_b32 s3, v254, 26
	s_branch .LBB0_158

; #define PG8_STAGE(bufoff, gbase, voff) do { _Pragma("unroll") for (int _i = 0; _i < 2; ++_i) \
;         __builtin_amdgcn_global_load_lds((const unsigned*)((const char*)(gbase) + (voff)[_i]), (PG8_LAS unsigned*)(lds + (bufoff) + ldsw + _i * 8192), 16, 0, 0); } while (0)
; #define PG8_WAIT_V(n) asm volatile("s_waitcnt vmcnt(" #n ")" ::: "memory")
; #define PG8_BAR __builtin_amdgcn_s_barrier()
; template <class Epi, class Sched, bool ALIGN_EPI = false, bool SP2 = false>
; __device__ __forceinline__ void gemm_phase(PG8_LAS unsigned char* lds, const Gemm g, const Sched& S, const Epi& E) {
;     ...
;     const char* cA = (const char*)g.A + (size_t)cur.pm * tstepA; const char* cB = (const char*)g.Bt + (size_t)cur.pn * tstepB;
;     S.a_ready(cur);
;     if constexpr (SP2) {
;         PG8_STAGE(PG8_SB(0, 0), cB, voffB); PG8_STAGE(PG8_SB(0, 1), cB + hstepB, voffB); PG8_STAGE(PG8_SA(0, 0), cA, voffA); PG8_STAGE(PG8_SA(0, 1), cA + hstepA, voffA);
;         if (wr == 1) PG8_BAR;
;         PG8_WAIT_V(2); PG8_BAR;
;         PG8_STAGE(PG8_SB(1, 0), cB + kstepB, voffB); PG8_STAGE(PG8_SA(1, 0), cA + kstepA, voffA); PG8_STAGE(PG8_SB(1, 1), cB + hstepB + kstepB, voffB);
;         PG8_WAIT_V(6); PG8_BAR;
.LBB0_244:
	v_and_b32_e32 v11, 48, v4
	v_lshlrev_b32_e32 v12, 6, v4
	s_movk_i32 s11, 0x3c0
	v_lshlrev_b32_e32 v4, 2, v4
	s_lshl_b32 s57, s2, 6
	s_lshl_b32 s2, s2, 13
	v_and_or_b32 v11, v12, s11, v11
	v_and_b32_e32 v4, 32, v4
	v_bitop3_b32 v12, v11, s2, v4 bitop3:0xde
	s_lshl_b32 s2, s3, 5
	s_and_b32 s58, s2, 0x60
	s_add_i32 m0, s22, 0x18000
	v_lshl_add_u64 v[2:3], v[2:3], 0, s[36:37]
	s_lshl_b32 s2, s58, 7
	v_readfirstlane_b32 s100, v232
	s_nop 3
	s_cmp_ge_u32 s100, 0x100
	s_cbranch_scc0 .Lsp_skip1
	s_setprio 1
.Lsp_skip1:
	s_waitcnt vmcnt(2)
	s_barrier
	global_load_lds_dwordx4 v[2:3], off
	s_add_i32 m0, s22, 0x1a000
	v_bitop3_b32 v97, s2, v11, v4 bitop3:0xf6
	s_add_u32 s2, s42, 0x400000
	v_mov_b32_e32 v135, v96
	v_lshl_add_u64 v[0:1], v[0:1], 0, s[36:37]
	s_addc_u32 s3, s43, 0
	s_add_i32 s59, s22, 0x8000
	v_mov_b32_e32 v139, v96
	global_load_lds_dwordx4 v[0:1], off
	v_lshl_add_u64 v[0:1], s[2:3], 0, v[134:135]
	s_mov_b32 m0, s59
	s_add_i32 s96, s22, 0xa000
	global_load_lds_dwordx4 v[0:1], off
	v_lshl_add_u64 v[0:1], s[2:3], 0, v[138:139]
	s_add_u32 s2, s24, 0x40080
	s_mov_b32 m0, s96
	s_addc_u32 s3, s25, 0
	global_load_lds_dwordx4 v[0:1], off
	s_add_i32 m0, s22, 0x1c000
	v_lshl_add_u64 v[0:1], s[2:3], 0, v[136:137]
	global_load_lds_dwordx4 v[0:1], off
	v_lshl_add_u64 v[0:1], s[2:3], 0, v[140:141]
	s_add_i32 m0, s22, 0x1e000
	s_cmpk_lt_u32 s4, 0x100
	global_load_lds_dwordx4 v[0:1], off
	v_lshlrev_b32_e32 v0, 10, v8
	v_and_b32_e32 v0, 0xfffff800, v0
	v_lshl_add_u32 v0, v9, 7, v0
	v_and_b32_e32 v1, 1, v8
	v_lshl_or_b32 v0, v1, 6, v0
	v_lshl_add_u32 v142, v10, 1, v0
	v_lshlrev_b32_e32 v0, 10, v5
	s_cselect_b64 s[2:3], -1, 0
	v_and_b32_e32 v0, 0xfffff800, v0
	s_waitcnt vmcnt(6)
	v_writelane_b32 v255, s2, 33
	v_lshl_add_u32 v0, v6, 7, v0
	v_and_b32_e32 v1, 1, v5
	v_writelane_b32 v255, s3, 34
	v_lshl_or_b32 v0, v1, 6, v0
	v_readlane_b32 s2, v254, 25
	v_mov_b32_e32 v143, v96
	v_lshl_add_u32 v144, v7, 1, v0
	v_mov_b32_e32 v145, v96
	s_mov_b32 s97, 0
	v_add_u32_e32 v151, 0, v12
	s_mov_b32 s4, s2
	v_readlane_b32 s26, v254, 9
	s_barrier
	v_readlane_b32 s3, v254, 26
	s_branch .LBB0_247

; #define PG8_STAGE(bufoff, gbase, voff) do { _Pragma("unroll") for (int _i = 0; _i < 2; ++_i) \
;         __builtin_amdgcn_global_load_lds((const unsigned*)((const char*)(gbase) + (voff)[_i]), (PG8_LAS unsigned*)(lds + (bufoff) + ldsw + _i * 8192), 16, 0, 0); } while (0)
; #define PG8_WAIT_V(n) asm volatile("s_waitcnt vmcnt(" #n ")" ::: "memory")
; #define PG8_BAR __builtin_amdgcn_s_barrier()
; template <class Epi, class Sched, bool ALIGN_EPI = false, bool SP2 = false>
; __device__ __forceinline__ void gemm_phase(PG8_LAS unsigned char* lds, const Gemm g, const Sched& S, const Epi& E) {
;     ...
;     const char* cA = (const char*)g.A + (size_t)cur.pm * tstepA; const char* cB = (const char*)g.Bt + (size_t)cur.pn * tstepB;
;     S.a_ready(cur);
;     if constexpr (SP2) {
;         PG8_STAGE(PG8_SB(0, 0), cB, voffB); PG8_STAGE(PG8_SB(0, 1), cB + hstepB, voffB); PG8_STAGE(PG8_SA(0, 0), cA, voffA); PG8_STAGE(PG8_SA(0, 1), cA + hstepA, voffA);
;         if (wr == 1) PG8_BAR;
;         PG8_WAIT_V(2); PG8_BAR;
;         PG8_STAGE(PG8_SB(1, 0), cB + kstepB, voffB); PG8_STAGE(PG8_SA(1, 0), cA + kstepA, voffA); PG8_STAGE(PG8_SB(1, 1), cB + hstepB + kstepB, voffB);
;         PG8_WAIT_V(6); PG8_BAR;
.LBB0_331:
	s_lshr_b32 s8, s2, 6
	s_lshl_b32 s2, s3, 6
	v_writelane_b32 v255, s2, 5
	v_and_b32_e32 v15, 48, v14
	s_lshl_b32 s2, s3, 13
	v_lshlrev_b32_e32 v16, 6, v14
	s_movk_i32 s3, 0x3c0
	v_lshlrev_b32_e32 v14, 2, v14
	s_and_b32 s39, s0, 3
	v_and_or_b32 v15, v16, s3, v15
	v_and_b32_e32 v14, 32, v14
	v_bitop3_b32 v16, v15, s2, v14 bitop3:0xde
	s_lshl_b32 s2, s39, 5
	s_add_i32 m0, s97, 0x18000
	v_lshl_add_u64 v[0:1], v[0:1], 0, s[36:37]
	v_writelane_b32 v255, s2, 31
	s_lshl_b32 s2, s39, 12
	v_readfirstlane_b32 s100, v232
	s_nop 3
	s_cmp_ge_u32 s100, 0x100
	s_cbranch_scc0 .Lsp_skip2
	s_setprio 1
.Lsp_skip2:
	s_waitcnt vmcnt(2)
	s_barrier
	global_load_lds_dwordx4 v[0:1], off
	s_add_i32 m0, s97, 0x1a000
	v_bitop3_b32 v97, v15, s2, v14 bitop3:0xde
	s_add_u32 s2, s24, s34
	v_mov_b32_e32 v165, v96
	v_lshl_add_u64 v[0:1], v[2:3], 0, s[36:37]
	s_addc_u32 s3, s25, s35
	s_add_i32 s6, s97, 0x8000
	v_mov_b32_e32 v161, v96
	global_load_lds_dwordx4 v[0:1], off
	v_lshl_add_u64 v[0:1], s[2:3], 0, v[164:165]
	s_mov_b32 m0, s6
	s_add_i32 s56, s97, 0xa000
	global_load_lds_dwordx4 v[0:1], off
	v_lshl_add_u64 v[0:1], s[2:3], 0, v[160:161]
	s_mov_b32 m0, s56
	s_add_i32 s57, s8, -2
	global_load_lds_dwordx4 v[0:1], off
	s_add_i32 m0, s97, 0x1c000
	v_lshl_add_u64 v[0:1], v[4:5], 0, s[36:37]
	global_load_lds_dwordx4 v[0:1], off
	v_lshl_add_u64 v[0:1], v[6:7], 0, s[36:37]
	s_add_i32 m0, s97, 0x1e000
	s_cmpk_lt_u32 s1, 0x100
	global_load_lds_dwordx4 v[0:1], off
	s_cselect_b64 s[2:3], -1, 0
	v_writelane_b32 v255, s2, 33
	s_bfe_u32 s1, s0, 0x10001
	s_lshl_b32 s0, s0, 6
	v_writelane_b32 v255, s3, 34
	v_writelane_b32 v255, s1, 9
	s_and_b32 s0, s0, 64
	v_readlane_b32 s1, v255, 15
	s_add_u32 s11, s1, s0
	v_readlane_b32 s0, v255, 16
	s_addc_u32 s9, s0, 0
	s_cmp_eq_u64 s[60:61], 0
	s_cselect_b64 s[54:55], -1, 0
	s_cmp_lg_u64 s[60:61], 0
	s_cselect_b64 s[16:17], -1, 0
	s_lshl_b32 s49, s34, 1
	v_and_b32_e32 v0, 1, v8
	v_mov_b32_e32 v2, 1
	s_add_u32 s0, s34, s98
	v_lshlrev_b32_e32 v0, 6, v0
	v_lshlrev_b32_sdwa v1, v2, sext(v9) dst_sel:DWORD dst_unused:UNUSED_PAD src0_sel:DWORD src1_sel:WORD_0
	s_addc_u32 s1, s35, 0
	v_add3_u32 v0, v10, v0, v1
	v_mov_b32_e32 v1, v96
	v_lshl_add_u64 v[166:167], s[0:1], 0, v[0:1]
	v_and_b32_e32 v0, 1, v11
	s_waitcnt vmcnt(6)
	v_lshlrev_b32_e32 v0, 6, v0
	v_lshlrev_b32_sdwa v1, v2, sext(v12) dst_sel:DWORD dst_unused:UNUSED_PAD src0_sel:DWORD src1_sel:WORD_0
	v_add3_u32 v0, v13, v0, v1
	v_mov_b32_e32 v1, v96
	s_mov_b32 s31, s30
	s_mov_b32 s50, s30
	s_mov_b32 s51, s30
	v_lshl_add_u64 v[168:169], s[0:1], 0, v[0:1]
	s_mov_b32 s99, 0
	v_add_u32_e32 v188, 0, v16
	v_readlane_b32 s4, v254, 12
	v_readlane_b32 s53, v254, 8
	s_barrier
	s_branch .LBB0_334

; #define PG8_STAGE(bufoff, gbase, voff) do { _Pragma("unroll") for (int _i = 0; _i < 2; ++_i) \
;         __builtin_amdgcn_global_load_lds((const unsigned*)((const char*)(gbase) + (voff)[_i]), (PG8_LAS unsigned*)(lds + (bufoff) + ldsw + _i * 8192), 16, 0, 0); } while (0)
; #define PG8_WAIT_V(n) asm volatile("s_waitcnt vmcnt(" #n ")" ::: "memory")
; #define PG8_BAR __builtin_amdgcn_s_barrier()
; template <class Epi, class Sched, bool ALIGN_EPI = false, bool SP2 = false>
; __device__ __forceinline__ void gemm_phase(PG8_LAS unsigned char* lds, const Gemm g, const Sched& S, const Epi& E) {
;     ...
;     const char* cA = (const char*)g.A + (size_t)cur.pm * tstepA; const char* cB = (const char*)g.Bt + (size_t)cur.pn * tstepB;
;     S.a_ready(cur);
;     if constexpr (SP2) {
;         PG8_STAGE(PG8_SB(0, 0), cB, voffB); PG8_STAGE(PG8_SB(0, 1), cB + hstepB, voffB); PG8_STAGE(PG8_SA(0, 0), cA, voffA); PG8_STAGE(PG8_SA(0, 1), cA + hstepA, voffA);
;         if (wr == 1) PG8_BAR;
;         PG8_WAIT_V(2); PG8_BAR;
;         PG8_STAGE(PG8_SB(1, 0), cB + kstepB, voffB); PG8_STAGE(PG8_SA(1, 0), cA + kstepA, voffA); PG8_STAGE(PG8_SB(1, 1), cB + hstepB + kstepB, voffB);
;         PG8_WAIT_V(6); PG8_BAR;
.LBB0_472:
	s_and_b32 s10, s2, 3
	s_add_i32 m0, s23, 0x18000
	v_lshl_add_u64 v[2:3], v[2:3], 0, s[36:37]
	s_lshl_b32 s48, s3, 6
	s_lshl_b32 s3, s3, 13
	s_lshl_b32 s10, s10, 12
	v_readfirstlane_b32 s100, v232
	s_nop 3
	s_cmp_ge_u32 s100, 0x100
	s_cbranch_scc0 .Lsp_skip3
	s_setprio 1
.Lsp_skip3:
	s_waitcnt vmcnt(2)
	s_barrier
	global_load_lds_dwordx4 v[2:3], off
	s_add_i32 m0, s23, 0x1a000
	s_add_u32 s16, s34, 0x400000
	v_mov_b32_e32 v131, v96
	v_lshl_add_u64 v[0:1], v[0:1], 0, s[36:37]
	s_addc_u32 s17, s35, 0
	s_add_i32 s49, s23, 0x8000
	v_mov_b32_e32 v135, v96
	global_load_lds_dwordx4 v[0:1], off
	v_lshl_add_u64 v[0:1], s[16:17], 0, v[130:131]
	s_mov_b32 m0, s49
	s_add_i32 s50, s23, 0xa000
	global_load_lds_dwordx4 v[0:1], off
	v_lshl_add_u64 v[0:1], s[16:17], 0, v[134:135]
	s_add_u32 s16, s0, 0x40080
	s_mov_b32 m0, s50
	s_addc_u32 s17, s1, 0
	global_load_lds_dwordx4 v[0:1], off
	s_add_i32 m0, s23, 0x1c000
	v_lshl_add_u64 v[0:1], s[16:17], 0, v[132:133]
	global_load_lds_dwordx4 v[0:1], off
	v_lshl_add_u64 v[0:1], s[16:17], 0, v[136:137]
	s_add_i32 m0, s23, 0x1e000
	s_movk_i32 s11, 0x3c0
	global_load_lds_dwordx4 v[0:1], off
	v_and_b32_e32 v0, 48, v4
	v_lshlrev_b32_e32 v1, 6, v4
	v_and_or_b32 v0, v1, s11, v0
	v_lshlrev_b32_e32 v1, 2, v4
	v_and_b32_e32 v1, 32, v1
	v_bitop3_b32 v2, v0, s3, v1 bitop3:0xde
	v_bitop3_b32 v97, v0, s10, v1 bitop3:0xde
	v_lshlrev_b32_e32 v0, 10, v8
	v_and_b32_e32 v0, 0xfffff800, v0
	v_lshl_add_u32 v0, v9, 7, v0
	v_and_b32_e32 v1, 1, v8
	v_lshl_or_b32 v0, v1, 6, v0
	s_cmpk_lt_u32 s28, 0x100
	v_lshl_add_u32 v138, v10, 1, v0
	v_lshlrev_b32_e32 v0, 10, v5
	s_cselect_b64 s[16:17], -1, 0
	s_bfe_u32 s51, s2, 0x10001
	s_lshl_b32 s2, s2, 6
	v_and_b32_e32 v0, 0xfffff800, v0
	s_waitcnt vmcnt(6)
	s_and_b32 s2, s2, 64
	v_readlane_b32 s10, v255, 11
	v_lshl_add_u32 v0, v6, 7, v0
	v_and_b32_e32 v1, 1, v5
	v_readlane_b32 s11, v255, 12
	s_add_u32 s52, s10, s2
	v_lshl_or_b32 v0, v1, 6, v0
	v_readlane_b32 s2, v254, 29
	s_addc_u32 s53, s11, 0
	v_mov_b32_e32 v139, v96
	v_lshl_add_u32 v140, v7, 1, v0
	v_mov_b32_e32 v141, v96
	s_mov_b32 s54, 0
	v_add_u32_e32 v156, 0, v2
	s_mov_b32 s56, s2
	v_readlane_b32 s55, v254, 15
	s_barrier
	v_readlane_b32 s3, v254, 30
	s_branch .LBB0_475
